# indexer score loop: quad-coalesced K-tile loads + wave-private LDS transpose to MFMA layout
# baseline (speedup 1.0000x reference)
; #define LAS __attribute__((address_space(3)))
; __device__ __forceinline__ void indexer_phase(const bf16_t* PJ, float* rk, unsigned short* SEL, LAS unsigned char* lds) {
;     ...
;     constexpr int AUX0 = 131072, AUXW = 3072;
;     LAS unsigned* hist = (LAS unsigned*)(lds + AUX0 + wid * AUXW);
;     LAS unsigned short* listA = (LAS unsigned short*)(lds + AUX0 + wid * AUXW + 2080);
;     LAS float* pmm = (LAS float*)(lds + AUX0 + NWAVE * AUXW);
;     for (int gl = blockIdx.x; gl < TOK / 8; gl += gridDim.x) {
;         const int b = gl >> 9, jj = gl & 511, t0 = (jj < 256 ? jj : 767 - jj) * 8;
;         const size_t rowbase = (size_t)b * SEQ;
;         const int t = t0 + wid;
;         unsigned short* selrow = SEL + (rowbase + t) * 256;
;         if (t0 + 7 < 256) {
; #pragma unroll
;             for (int i = 0; i < 4; ++i) { const int s = lane + 64 * i; selrow[s] = (unsigned short)(s <= t ? s : 0); }
;             continue;
;         }
;         {
;             const int g = r32 >> 3, hp = (r32 >> 2) & 1, ii = r32 & 3, tq = 2 * hp + (g >> 1), head = 4 * (g & 1) + ii;
;             bf16x8 af[2][4]; float wq[2][2][8];
; #pragma unroll
;             for (int rt = 0; rt < 2; ++rt) {
;                 const bf16_t* qp = PJ + (rowbase + t0 + 4 * rt + tq) * PROJ_LD + PJ_QI + head * 64 + hi * 8;
; #pragma unroll
;                 for (int kk = 0; kk < 4; ++kk) af[rt][kk] = *(const bf16x8*)(qp + kk * 16);
; #pragma unroll
;                 for (int qq = 0; qq < 2; ++qq) { const u32x4 w = *(const u32x4*)(PJ + (rowbase + t0 + 4 * rt + 2 * hi + qq) * PROJ_LD + PJ_WI);
;                     const float sc = 0.35355339059327373f;
;                     wq[rt][qq][0] = bflo(w.x) * sc; wq[rt][qq][1] = bfhi(w.x) * sc; wq[rt][qq][2] = bflo(w.y) * sc; wq[rt][qq][3] = bfhi(w.y) * sc;
;                     wq[rt][qq][4] = bflo(w.z) * sc; wq[rt][qq][5] = bfhi(w.z) * sc; wq[rt][qq][6] = bflo(w.w) * sc; wq[rt][qq][7] = bfhi(w.w) * sc; }
;             }
;             float rmax[2][2], rmin[2][2];
; #pragma unroll
;             for (int rt = 0; rt < 2; ++rt)
; #pragma unroll
;                 for (int qq = 0; qq < 2; ++qq) { rmax[rt][qq] = -INFINITY; rmin[rt][qq] = INFINITY; }
;             const int nkt = (t0 + 8 + 31) >> 5;
;             const bf16_t* kbase = PJ + (rowbase + r32) * PROJ_LD + PJ_KI + hi * 8;
;             bf16x8 bcur[4], bnxt[4];
;             int kt = wid;
; #pragma unroll
.LBB0_861:
	s_cmpk_gt_i32 s76, 0xfff
	s_cbranch_scc1 .LBB0_1030
	v_writelane_b32 v255, s60, 15
	s_mul_i32 s0, s33, 0xc00
	s_add_i32 s94, s0, 0
	v_writelane_b32 v255, s61, 16
	v_writelane_b32 v255, s59, 17
	s_add_i32 s94, s94, 0x20000
	v_writelane_b32 v255, s82, 18
	s_add_u32 s4, s10, 0x1e400000
	s_addc_u32 s5, s11, 0
	v_writelane_b32 v255, s83, 19
	s_lshl_b32 s0, s33, 5
	s_mul_i32 s2, s33, 0x2c000
	v_writelane_b32 v255, s0, 20
	s_mul_hi_i32 s3, s0, 0x1600
	v_lshrrev_b32_e32 v1, 5, v108
	v_writelane_b32 v255, s2, 21
	v_lshrrev_b32_e32 v2, 1, v6
	v_bfe_u32 v3, v6, 4, 1
	v_lshlrev_b32_e32 v116, 1, v1
	v_writelane_b32 v255, s3, 22
	s_lshl_b32 s0, s33, 3
	v_and_or_b32 v112, v2, 2, v3
	v_writelane_b32 v255, s0, 23
	v_or_b32_e32 v3, s0, v116
	s_lshl_b32 s0, s33, 14
	s_add_i32 s96, s0, 0
	v_mov_b32_e32 v4, 0x200
	v_lshl_add_u32 v119, v108, 5, s94
	s_movk_i32 s0, 0xffe4
	v_and_b32_e32 v0, 3, v6
	v_and_or_b32 v113, v6, 7, v4
	v_mad_i32_i24 v158, v108, s0, v119
	v_or_b32_e32 v4, 0x200, v108
	s_movk_i32 s0, 0x208
	v_and_or_b32 v0, v2, 4, v0
	v_cmp_gt_u32_e64 s[10:11], s0, v4
	s_lshl_b32 s0, s33, 7
	v_and_b32_e32 v110, 31, v6
	v_lshlrev_b32_e32 v0, 6, v0
	v_lshlrev_b32_e32 v2, 3, v1
	v_lshlrev_b32_e32 v118, 2, v108
	v_lshl_add_u32 v1, v1, 15, s0
	v_lshlrev_b32_e32 v117, 3, v108
	v_add_u32_e32 v159, v158, v118
	v_lshlrev_b32_e32 v160, 3, v3
	v_sub_u32_e32 v3, 0, v118
	v_lshl_or_b32 v1, v110, 2, v1
	v_lshlrev_b32_e32 v114, 1, v0
	v_mbcnt_hi_u32_b32 v180, -1, v195
	v_mov_b32_e32 v0, 0x80
	v_mov_b32_e32 v115, 0
	s_movk_i32 s7, 0x1600
	v_cmp_eq_u32_e64 s[8:9], 0, v110
	v_lshl_add_u32 v111, v108, 4, s96
	v_or_b32_e32 v121, 0x100, v108
	v_or_b32_e32 v120, 1, v116
	v_cmp_eq_u32_e64 s[12:13], 63, v108
	v_cmp_gt_u32_e64 s[14:15], 62, v108
	v_cmp_gt_u32_e64 s[16:17], 60, v108
	v_cmp_gt_u32_e64 s[18:19], 56, v108
	v_cmp_gt_u32_e64 s[20:21], 48, v108
	v_cmp_gt_u32_e64 s[22:23], 32, v108
	v_or_b32_e32 v161, 7, v117
	v_or_b32_e32 v162, 6, v117
	v_or_b32_e32 v163, 5, v117
	v_or_b32_e32 v164, 4, v117
	v_or_b32_e32 v165, 3, v117
	v_or_b32_e32 v166, 2, v117
	v_or_b32_e32 v167, 1, v117
	v_or_b32_e32 v168, 64, v108
	v_or_b32_e32 v169, 0x80, v108
	v_or_b32_e32 v170, 0xc0, v108
	v_mov_b32_e32 v109, v108
	v_add_u32_e32 v171, 0, v1
	v_or_b32_e32 v172, 0x100, v118
	v_add_u32_e32 v173, s96, v118
	v_lshlrev_b32_e32 v122, 1, v2
	s_movk_i32 s44, 0x1000
	s_mov_b32 s58, 0x3eb504f3
	s_mov_b32 s45, 0x43ff8000
	v_mov_b32_e32 v174, 1
	v_lshlrev_b32_e32 v175, 1, v118
	v_lshlrev_b32_e32 v176, 1, v108
	v_mov_b32_e32 v177, 0x1600
	v_mov_b32_e32 v178, 0xff800000
	v_mov_b32_e32 v179, 0x7f800000
	v_lshl_or_b32 v181, v180, 2, v0
	v_add_u32_e32 v182, v159, v3
	s_mov_b32 s2, s76
	v_lshrrev_b32_e32 v222, 2, v108
	v_and_b32_e32 v223, 31, v108
	v_sub_u32_e32 v218, v222, v223
	v_mul_i32_i24_e32 v218, 0x1600, v218
	v_and_b32_e32 v224, 3, v108
	v_lshrrev_b32_e32 v225, 5, v108
	v_sub_u32_e32 v219, v224, v225
	v_lshl_add_u32 v218, v219, 4, v218
	v_ashrrev_i32_e32 v219, 31, v218
	v_bfe_u32 v226, v108, 4, 2
	v_xor_b32_e32 v226, v224, v226
	v_lshlrev_b32_e32 v226, 4, v226
	v_lshl_add_u32 v222, v222, 6, v226
	v_add_u32_e32 v222, s94, v222
	v_bfe_u32 v226, v108, 2, 2
	v_xor_b32_e32 v226, v225, v226
	v_lshlrev_b32_e32 v226, 4, v226
	v_lshl_add_u32 v223, v223, 6, v226
	v_add_u32_e32 v223, s94, v223
	v_xor_b32_e32 v224, 32, v223
	s_branch .LBB0_864

; __device__ __forceinline__ void indexer_phase(const bf16_t* PJ, float* rk, unsigned short* SEL, LAS unsigned char* lds) {
;     ...
;             const int g = r32 >> 3, hp = (r32 >> 2) & 1, ii = r32 & 3, tq = 2 * hp + (g >> 1), head = 4 * (g & 1) + ii;
;             bf16x8 af[2][4]; float wq[2][2][8];
; #pragma unroll
;             for (int rt = 0; rt < 2; ++rt) {
;                 const bf16_t* qp = PJ + (rowbase + t0 + 4 * rt + tq) * PROJ_LD + PJ_QI + head * 64 + hi * 8;
; #pragma unroll
;                 for (int kk = 0; kk < 4; ++kk) af[rt][kk] = *(const bf16x8*)(qp + kk * 16);
; #pragma unroll
;                 for (int qq = 0; qq < 2; ++qq) { const u32x4 w = *(const u32x4*)(PJ + (rowbase + t0 + 4 * rt + 2 * hi + qq) * PROJ_LD + PJ_WI);
;                     const float sc = 0.35355339059327373f;
;                     wq[rt][qq][0] = bflo(w.x) * sc; wq[rt][qq][1] = bfhi(w.x) * sc; wq[rt][qq][2] = bflo(w.y) * sc; wq[rt][qq][3] = bfhi(w.y) * sc;
;                     wq[rt][qq][4] = bflo(w.z) * sc; wq[rt][qq][5] = bfhi(w.z) * sc; wq[rt][qq][6] = bflo(w.w) * sc; wq[rt][qq][7] = bfhi(w.w) * sc; }
;             }
;             float rmax[2][2], rmin[2][2];
; #pragma unroll
;             for (int rt = 0; rt < 2; ++rt)
; #pragma unroll
;                 for (int qq = 0; qq < 2; ++qq) { rmax[rt][qq] = -INFINITY; rmin[rt][qq] = INFINITY; }
;             const int nkt = (t0 + 8 + 31) >> 5;
;             const bf16_t* kbase = PJ + (rowbase + r32) * PROJ_LD + PJ_KI + hi * 8;
;             bf16x8 bcur[4], bnxt[4];
;             int kt = wid;
; #pragma unroll
;             for (int kk = 0; kk < 4; ++kk) bcur[kk] = *(const bf16x8*)(kbase + (size_t)(32 * kt) * PROJ_LD + kk * 16);
.LBB0_864:
	s_and_b32 s0, s2, 0x1ff
	s_ashr_i32 s24, s2, 9
	s_sub_i32 s1, 0x2ff, s0
	s_cmpk_lt_u32 s0, 0x100
	s_cselect_b32 s0, s0, s1
	s_lshl_b32 s1, s0, 3
	s_ashr_i32 s25, s24, 31
	s_add_i32 s77, s1, s33
	s_lshl_b64 s[26:27], s[24:25], 12
	s_ashr_i32 s3, s77, 31
	s_add_u32 s24, s26, s77
	s_addc_u32 s25, s27, s3
	s_lshl_b64 s[24:25], s[24:25], 9
	s_add_u32 s60, s4, s24
	s_addc_u32 s61, s5, s25
	s_cmp_gt_u32 s0, 31
	s_mov_b64 s[24:25], -1
	s_cbranch_scc0 .LBB0_1027
	s_add_i32 s0, s1, 39
	s_lshr_b32 s0, s0, 5
	s_cmp_ge_i32 s33, s0
	s_cbranch_scc1 .LBB0_873
	v_readlane_b32 s24, v255, 13
	s_add_u32 s3, s26, s1
	v_readlane_b32 s25, v255, 14
	v_or_b32_e32 v0, s3, v112
	s_addc_u32 s6, s27, 0
	v_mov_b64_e32 v[16:17], s[24:25]
	v_mad_u64_u32 v[0:1], s[24:25], v0, s7, v[16:17]
	v_mad_i32_i24 v1, s6, v177, v1
	v_lshl_add_u64 v[0:1], v[0:1], 0, v[114:115]
	v_mov_b32_e32 v123, v115
	v_lshl_add_u64 v[18:19], v[0:1], 0, v[122:123]
	v_or_b32_e32 v0, s3, v116
	v_add_co_u32_e32 v20, vcc, s44, v18
	v_mad_u64_u32 v[0:1], s[24:25], v0, s7, v[16:17]
	v_mad_i32_i24 v1, s6, v177, v1
	s_mov_b64 s[24:25], vcc
	v_add_co_u32_e32 v0, vcc, s44, v0
	v_or_b32_e32 v4, s3, v120
	s_nop 0
	v_addc_co_u32_e32 v1, vcc, 0, v1, vcc
	v_mad_u64_u32 v[4:5], s[28:29], v4, s7, v[16:17]
	s_or_b32 s3, s3, 4
	v_mad_i32_i24 v5, s6, v177, v5
	v_add_co_u32_e32 v4, vcc, s44, v4
	v_or_b32_e32 v8, s3, v116
	s_nop 0
	v_addc_co_u32_e32 v5, vcc, 0, v5, vcc
	v_mad_u64_u32 v[8:9], s[28:29], v8, s7, v[16:17]
	v_mad_i32_i24 v9, s6, v177, v9
	v_add_co_u32_e32 v8, vcc, s44, v8
	v_or_b32_e32 v12, s3, v120
	s_nop 0
	v_addc_co_u32_e32 v9, vcc, 0, v9, vcc
	s_mov_b64 s[30:31], 0x1100
	s_waitcnt lgkmcnt(0)
	v_mad_u64_u32 v[12:13], s[28:29], v12, s7, v[16:17]
	v_lshl_add_u64 v[22:23], v[18:19], 0, s[30:31]
	v_mad_i32_i24 v13, s6, v177, v13
	v_add_co_u32_e32 v12, vcc, s44, v12
	v_or_b32_e32 v18, s3, v112
	global_load_dwordx4 v[0:3], v[0:1], off offset:1408
	v_addc_co_u32_e32 v13, vcc, 0, v13, vcc
	v_addc_co_u32_e64 v21, vcc, 0, v19, s[24:25]
	v_mad_u64_u32 v[18:19], s[24:25], v18, s7, v[16:17]
	v_mad_i32_i24 v19, s6, v177, v19
	global_load_dwordx4 v[4:7], v[4:5], off offset:1408
	v_lshl_add_u64 v[18:19], v[18:19], 0, v[114:115]
	v_lshl_add_u64 v[18:19], v[18:19], 0, v[122:123]
	global_load_dwordx4 v[8:11], v[8:9], off offset:1408
	v_or_b32_e32 v190, s1, v116
	global_load_dwordx4 v[12:15], v[12:13], off offset:1408
	s_nop 0
	global_load_dwordx4 v[64:67], v[22:23], off offset:32
	global_load_dwordx4 v[68:71], v[22:23], off offset:64
	global_load_dwordx4 v[72:75], v[20:21], off offset:256
	global_load_dwordx4 v[76:79], v[22:23], off offset:96
	v_lshl_add_u64 v[20:21], v[18:19], 0, s[30:31]
	v_add_co_u32_e32 v22, vcc, s44, v18
	v_or_b32_e32 v18, s26, v110
	v_mad_u64_u32 v[16:17], s[24:25], v18, s7, v[16:17]
	v_mad_i32_i24 v17, s27, v177, v17
	v_lshl_add_u64 v[16:17], v[16:17], 0, v[122:123]
	s_mov_b64 s[24:25], 0x1500
	v_lshl_add_u64 v[124:125], v[16:17], 0, s[24:25]
	v_lshl_add_u64 v[216:217], v[218:219], 0, v[124:125]
	v_readlane_b32 s24, v255, 21
	v_readlane_b32 s25, v255, 22
	v_addc_co_u32_e32 v23, vcc, 0, v19, vcc
	s_nop 0
	v_lshl_add_u64 v[16:17], v[124:125], 0, s[24:25]
	global_load_dwordx4 v[80:83], v[20:21], off offset:32
	global_load_dwordx4 v[84:87], v[20:21], off offset:64
	global_load_dwordx4 v[96:99], v[16:17], off offset:96
	global_load_dwordx4 v[100:103], v[16:17], off offset:64
	global_load_dwordx4 v[104:107], v[16:17], off offset:32
	s_nop 0
	global_load_dwordx4 v[16:19], v[16:17], off
	s_nop 0
	global_load_dwordx4 v[88:91], v[22:23], off offset:256
	global_load_dwordx4 v[92:95], v[20:21], off offset:96
	v_mov_b64_e32 v[54:55], v[34:35]
	v_mov_b64_e32 v[58:59], v[38:39]
	v_mov_b64_e32 v[62:63], v[42:43]
	v_mov_b64_e32 v[50:51], v[46:47]
	v_or_b32_e32 v191, 1, v190
	v_or_b32_e32 v192, 4, v190
	v_or_b32_e32 v193, 5, v190
	v_mov_b32_e32 v189, 0xff800000
	v_mov_b32_e32 v188, 0x7f800000
	v_mov_b32_e32 v196, v171
	v_readlane_b32 s6, v255, 20
	v_mov_b64_e32 v[52:53], v[32:33]
	v_mov_b64_e32 v[56:57], v[36:37]
	v_mov_b64_e32 v[60:61], v[40:41]
	v_mov_b64_e32 v[48:49], v[44:45]
	v_mov_b32_e32 v186, 0x7f800000
	v_mov_b32_e32 v184, 0x7f800000
	v_mov_b32_e32 v123, 0x7f800000
	v_mov_b32_e32 v187, 0xff800000
	v_mov_b32_e32 v185, 0xff800000
	v_mov_b32_e32 v183, 0xff800000
	s_mov_b32 s1, s33
	s_waitcnt vmcnt(15)
	v_and_b32_e32 v20, 0xffff0000, v0
	v_lshlrev_b32_e32 v21, 16, v0
	v_and_b32_e32 v0, 0xffff0000, v1
	v_lshlrev_b32_e32 v1, 16, v1
	v_pk_mul_f32 v[128:129], v[0:1], s[58:59] op_sel_hi:[1,0]
	v_and_b32_e32 v0, 0xffff0000, v3
	v_lshlrev_b32_e32 v1, 16, v3
	v_pk_mul_f32 v[132:133], v[0:1], s[58:59] op_sel_hi:[1,0]
	s_waitcnt vmcnt(14)
	v_and_b32_e32 v0, 0xffff0000, v4
	v_lshlrev_b32_e32 v1, 16, v4
	v_pk_mul_f32 v[134:135], v[0:1], s[58:59] op_sel_hi:[1,0]
	v_and_b32_e32 v0, 0xffff0000, v5
	v_lshlrev_b32_e32 v1, 16, v5
	v_pk_mul_f32 v[136:137], v[0:1], s[58:59] op_sel_hi:[1,0]
	v_and_b32_e32 v0, 0xffff0000, v6
	v_lshlrev_b32_e32 v1, 16, v6
	v_pk_mul_f32 v[138:139], v[0:1], s[58:59] op_sel_hi:[1,0]
	v_and_b32_e32 v0, 0xffff0000, v7
	v_lshlrev_b32_e32 v1, 16, v7
	v_pk_mul_f32 v[140:141], v[0:1], s[58:59] op_sel_hi:[1,0]
	s_waitcnt vmcnt(13)
	v_and_b32_e32 v0, 0xffff0000, v8
	v_lshlrev_b32_e32 v1, 16, v8
	v_pk_mul_f32 v[142:143], v[0:1], s[58:59] op_sel_hi:[1,0]
	v_and_b32_e32 v0, 0xffff0000, v9
	v_lshlrev_b32_e32 v1, 16, v9
	v_pk_mul_f32 v[144:145], v[0:1], s[58:59] op_sel_hi:[1,0]
	v_and_b32_e32 v0, 0xffff0000, v10
	v_lshlrev_b32_e32 v1, 16, v10
	v_pk_mul_f32 v[146:147], v[0:1], s[58:59] op_sel_hi:[1,0]
	v_and_b32_e32 v0, 0xffff0000, v11
	v_lshlrev_b32_e32 v1, 16, v11
	v_pk_mul_f32 v[148:149], v[0:1], s[58:59] op_sel_hi:[1,0]
	s_waitcnt vmcnt(12)
	v_and_b32_e32 v0, 0xffff0000, v12
	v_lshlrev_b32_e32 v1, 16, v12
	v_pk_mul_f32 v[150:151], v[0:1], s[58:59] op_sel_hi:[1,0]
	v_and_b32_e32 v0, 0xffff0000, v13
	v_lshlrev_b32_e32 v1, 16, v13
	v_pk_mul_f32 v[152:153], v[0:1], s[58:59] op_sel_hi:[1,0]
	v_and_b32_e32 v0, 0xffff0000, v14
	v_lshlrev_b32_e32 v1, 16, v14
	v_and_b32_e32 v22, 0xffff0000, v2
	v_lshlrev_b32_e32 v23, 16, v2
	v_pk_mul_f32 v[154:155], v[0:1], s[58:59] op_sel_hi:[1,0]
	v_and_b32_e32 v0, 0xffff0000, v15
	v_lshlrev_b32_e32 v1, 16, v15
	v_pk_mul_f32 v[126:127], v[20:21], s[58:59] op_sel_hi:[1,0]
	v_pk_mul_f32 v[130:131], v[22:23], s[58:59] op_sel_hi:[1,0]
	v_pk_mul_f32 v[156:157], v[0:1], s[58:59] op_sel_hi:[1,0]
	s_waitcnt vmcnt(0)

; #define LAS __attribute__((address_space(3)))
; __device__ __forceinline__ void indexer_phase(const bf16_t* PJ, float* rk, unsigned short* SEL, LAS unsigned char* lds) {
;     ...
;             while (kt < nkt) {
;                 const int kn = kt + NWAVE;
;                 if (kn < nkt) {
; #pragma unroll
;                     for (int kk = 0; kk < 4; ++kk) bnxt[kk] = *(const bf16x8*)(kbase + (size_t)(32 * kn) * PROJ_LD + kk * 16);
;                 }
;                 const int key = 32 * kt + r32;
; #pragma unroll
;                 for (int rt = 0; rt < 2; ++rt) {
;                     f32x16 acc = f32x16{};
; #pragma unroll
;                     for (int kk = 0; kk < 4; ++kk) acc = __builtin_amdgcn_mfma_f32_32x32x16_bf16(af[rt][kk], bcur[kk], acc, 0, 0, 0);
; #pragma unroll
;                     for (int qq = 0; qq < 2; ++qq) { float s = 0.f;
; #pragma unroll
;                         for (int e = 0; e < 8; ++e) s += wq[rt][qq][e] * fmaxf(acc[8 * qq + e], 0.f);
;                         ((LAS float*)lds)[(4 * rt + 2 * hi + qq) * 4096 + key] = s;
;                         const bool ok = key <= t0 + 4 * rt + 2 * hi + qq;
;                         rmax[rt][qq] = fmaxf(rmax[rt][qq], ok ? s : -INFINITY); rmin[rt][qq] = fminf(rmin[rt][qq], ok ? s : INFINITY); }
;                 }
; #pragma unroll
;                 for (int kk = 0; kk < 4; ++kk) bcur[kk] = bnxt[kk];
;                 kt = kn;
.LBB0_869:
	s_andn2_b64 vcc, exec, s[26:27]
	s_cbranch_vccnz .LBB0_871
	s_add_i32 s3, s6, 0x100
	s_add_i32 s32, s3, 16
	v_mad_i64_i32 v[0:1], s[26:27], s3, v177, v[216:217]
	v_mad_i64_i32 v[220:221], s[26:27], s32, v177, v[216:217]
	global_load_dwordx4 v[52:55], v[0:1], off
	global_load_dwordx4 v[56:59], v[220:221], off
	global_load_dwordx4 v[60:63], v[0:1], off offset:64
	global_load_dwordx4 v[48:51], v[220:221], off offset:64
.LBB0_871:
	s_waitcnt lgkmcnt(0)
	v_mfma_f32_32x32x16_bf16 v[0:15], v[72:75], v[16:19], 0
	v_add_u32_e32 v197, s6, v110
	v_cmp_gt_i32_e32 vcc, v197, v190
	v_max_f32_e32 v20, v189, v189
	v_max_f32_e32 v21, v188, v188
	v_mfma_f32_32x32x16_bf16 v[0:15], v[64:67], v[104:107], v[0:15]
	v_mfma_f32_32x32x16_bf16 v[0:15], v[68:71], v[100:103], v[0:15]
	v_mfma_f32_32x32x16_bf16 v[0:15], v[76:79], v[96:99], v[0:15]
	s_nop 11
	v_max_f32_e32 v0, v0, v0
	v_max_f32_e32 v22, v1, v1
	v_max_f32_e32 v1, 0, v0
	v_max_f32_e32 v0, 0, v22
	v_max_f32_e32 v2, v2, v2
	v_max_f32_e32 v23, v3, v3
	v_pk_mul_f32 v[0:1], v[126:127], v[0:1]
	v_max_f32_e32 v3, 0, v2
	v_max_f32_e32 v2, 0, v23
	v_add_f32_e32 v1, 0, v1
	v_max_f32_e32 v4, v4, v4
	v_max_f32_e32 v24, v5, v5
	v_pk_mul_f32 v[2:3], v[128:129], v[2:3]
	v_add_f32_e32 v0, v0, v1
	v_max_f32_e32 v5, 0, v4
	v_max_f32_e32 v4, 0, v24
	v_add_f32_e32 v0, v3, v0
	v_max_f32_e32 v6, v6, v6
	v_max_f32_e32 v25, v7, v7
	v_pk_mul_f32 v[4:5], v[130:131], v[4:5]
	v_add_f32_e32 v0, v2, v0
	v_max_f32_e32 v7, 0, v6
	v_max_f32_e32 v6, 0, v25
	v_add_f32_e32 v0, v5, v0
	v_pk_mul_f32 v[6:7], v[132:133], v[6:7]
	v_add_f32_e32 v0, v4, v0
	v_add_f32_e32 v0, v7, v0
	v_add_f32_e32 v2, v6, v0
	v_max_f32_e32 v8, v8, v8
	v_max_f32_e32 v26, v9, v9
	v_cndmask_b32_e32 v0, v2, v178, vcc
	v_cndmask_b32_e32 v1, v2, v179, vcc
	v_max_f32_e32 v9, 0, v8
	v_max_f32_e32 v8, 0, v26
	v_max_f32_e32 v189, v20, v0
	v_min_f32_e32 v188, v21, v1
	s_nop 0
	v_mfma_f32_32x32x16_bf16 v[16:31], v[88:91], v[16:19], 0
	v_mul_f32_e64 v8, v134, v8
	v_mul_f32_e64 v9, v135, v9
	v_cmp_gt_i32_e32 vcc, v197, v191
	v_add_f32_e32 v0, 0, v9
	v_add_f32_e32 v3, v8, v0
	v_max_f32_e32 v0, v10, v10
	v_max_f32_e32 v1, 0, v0
	v_max_f32_e32 v0, v11, v11
	v_mfma_f32_32x32x16_bf16 v[16:31], v[80:83], v[104:107], v[16:31]
	v_max_f32_e32 v0, 0, v0
	v_mul_f32_e64 v0, v136, v0
	v_mul_f32_e64 v1, v137, v1
	v_add_f32_e32 v1, v1, v3
	v_add_f32_e32 v3, v0, v1
	v_max_f32_e32 v0, v12, v12
	v_max_f32_e32 v1, 0, v0
	v_mfma_f32_32x32x16_bf16 v[16:31], v[84:87], v[100:103], v[16:31]
	v_max_f32_e32 v0, v13, v13
	v_max_f32_e32 v0, 0, v0
	v_mul_f32_e64 v0, v138, v0
	v_mul_f32_e64 v1, v139, v1
	v_add_f32_e32 v1, v1, v3
	v_add_f32_e32 v3, v0, v1
	v_max_f32_e32 v0, v14, v14
	s_nop 0
	v_mfma_f32_32x32x16_bf16 v[16:31], v[92:95], v[96:99], v[16:31]
	v_max_f32_e32 v1, 0, v0
	v_max_f32_e32 v0, v15, v15
	v_max_f32_e32 v0, 0, v0
	v_mul_f32_e64 v0, v140, v0
	v_mul_f32_e64 v1, v141, v1
	v_add_f32_e32 v1, v1, v3
	v_add_f32_e32 v0, v0, v1
	ds_write2st64_b32 v196, v2, v0 offset1:64
	v_cndmask_b32_e32 v1, v0, v178, vcc
	v_max_f32_e32 v2, v187, v187
	v_max_f32_e32 v187, v2, v1
	v_cndmask_b32_e32 v0, v0, v179, vcc
	v_max_f32_e32 v1, v186, v186
	v_min_f32_e32 v186, v1, v0
	v_max_f32_e32 v0, v16, v16
	v_max_f32_e32 v1, 0, v0
	v_max_f32_e32 v0, v17, v17
	v_max_f32_e32 v0, 0, v0
	v_pk_mul_f32 v[0:1], v[142:143], v[0:1]
	v_cmp_gt_i32_e32 vcc, v197, v192
	v_add_f32_e32 v1, 0, v1
	v_add_f32_e32 v2, v0, v1
	v_max_f32_e32 v0, v18, v18
	v_max_f32_e32 v1, 0, v0
	v_max_f32_e32 v0, v19, v19
	v_max_f32_e32 v0, 0, v0
	v_pk_mul_f32 v[0:1], v[144:145], v[0:1]
	s_nop 0
	v_add_f32_e32 v1, v1, v2
	v_add_f32_e32 v2, v0, v1
	v_max_f32_e32 v0, v20, v20
	v_max_f32_e32 v1, 0, v0
	v_max_f32_e32 v0, v21, v21
	v_max_f32_e32 v0, 0, v0
	v_pk_mul_f32 v[0:1], v[146:147], v[0:1]
	s_nop 0
	v_add_f32_e32 v1, v1, v2
	v_add_f32_e32 v2, v0, v1
	v_max_f32_e32 v0, v22, v22
	v_max_f32_e32 v1, 0, v0
	v_max_f32_e32 v0, v23, v23
	v_max_f32_e32 v0, 0, v0
	v_pk_mul_f32 v[0:1], v[148:149], v[0:1]
	s_nop 0
	v_add_f32_e32 v1, v1, v2
	v_add_f32_e32 v0, v0, v1
	v_add_u32_e32 v1, 0x10000, v196
	ds_write_b32 v1, v0
	v_cndmask_b32_e32 v1, v0, v178, vcc
	v_max_f32_e32 v2, v185, v185
	v_max_f32_e32 v185, v2, v1
	v_cndmask_b32_e32 v0, v0, v179, vcc
	v_max_f32_e32 v1, v184, v184
	v_min_f32_e32 v184, v1, v0
	v_max_f32_e32 v0, v24, v24
	v_max_f32_e32 v1, 0, v0
	v_max_f32_e32 v0, v25, v25
	v_max_f32_e32 v0, 0, v0
	v_pk_mul_f32 v[0:1], v[150:151], v[0:1]
	v_cmp_gt_i32_e32 vcc, v197, v193
	v_add_f32_e32 v1, 0, v1
	v_add_f32_e32 v2, v0, v1
	v_max_f32_e32 v0, v26, v26
	v_max_f32_e32 v1, 0, v0
	v_max_f32_e32 v0, v27, v27
	v_max_f32_e32 v0, 0, v0
	v_pk_mul_f32 v[0:1], v[152:153], v[0:1]
	s_nop 0
	v_add_f32_e32 v1, v1, v2
	v_add_f32_e32 v2, v0, v1
	v_max_f32_e32 v0, v28, v28
	v_max_f32_e32 v1, 0, v0
	v_max_f32_e32 v0, v29, v29
	v_max_f32_e32 v0, 0, v0
	v_pk_mul_f32 v[0:1], v[154:155], v[0:1]
	s_nop 0
	v_add_f32_e32 v1, v1, v2
	v_add_f32_e32 v2, v0, v1
	v_max_f32_e32 v0, v30, v30
	v_max_f32_e32 v1, 0, v0
	v_max_f32_e32 v0, v31, v31
	v_max_f32_e32 v0, 0, v0
	v_pk_mul_f32 v[0:1], v[156:157], v[0:1]
	s_nop 0
	v_add_f32_e32 v1, v1, v2
	v_add_f32_e32 v0, v0, v1
	v_add_u32_e32 v1, 0x14000, v196
	ds_write_b32 v1, v0
	v_cndmask_b32_e32 v1, v0, v178, vcc
	v_max_f32_e32 v2, v183, v183
	v_max_f32_e32 v183, v2, v1
	v_cndmask_b32_e32 v0, v0, v179, vcc
	v_max_f32_e32 v1, v123, v123
	v_min_f32_e32 v123, v1, v0
	v_add_u32_e32 v196, 0x400, v196
	s_and_b64 vcc, exec, s[24:25]
	s_cbranch_vccnz .LBB0_874
	s_waitcnt vmcnt(0)
	ds_write_b128 v222, v[52:55]
	ds_write_b128 v222, v[56:59] offset:1024
	s_waitcnt lgkmcnt(0)
	ds_read_b128 v[16:19], v223
	ds_read_b128 v[104:107], v224
	s_waitcnt lgkmcnt(0)
	ds_write_b128 v222, v[60:63]
	ds_write_b128 v222, v[48:51] offset:1024
	s_waitcnt lgkmcnt(0)
	ds_read_b128 v[100:103], v223
	ds_read_b128 v[96:99], v224
	s_mov_b32 s6, s3
	s_branch .LBB0_867
